# static priority raise: NSA phase waves 4-7 at s_setprio 1 for the whole phase, per-segment flips removed
# baseline (speedup 1.0000x reference)
.LBB0_969:
	s_cmp_lt_i32 s94, 13
	s_cselect_b64 s[34:35], -1, 0
	s_and_b64 s[0:1], s[34:35], s[0:1]
	s_andn2_b64 vcc, exec, s[0:1]
	s_cbranch_vccnz .LBB0_1074
	v_readfirstlane_b32 s99, v129
	s_lshr_b32 s99, s99, 8
	s_cmp_eq_u32 s99, 0
	s_cbranch_scc1 .Lp12_prio_done
	s_setprio 1
.Lp12_prio_done:
	s_add_u32 s36, s92, 0x4000000
	s_addc_u32 s37, s93, 0
	s_cmpk_lt_i32 s2, 0x1000
	s_cselect_b64 s[0:1], -1, 0
	s_cmpk_gt_i32 s2, 0xfff
	v_lshrrev_b32_e32 v131, 6, v129
	s_cbranch_scc1 .LBB0_975
	s_ashr_i32 s3, s2, 3
	s_cmpk_lg_i32 s84, 0x100
	s_cbranch_scc1 .LBB0_983
	s_ashr_i32 s6, s2, 8
	s_cmp_gt_i32 s6, 1
	s_cbranch_scc0 .LBB0_976
	s_cmp_gt_u32 s6, 8
	s_cbranch_scc0 .LBB0_977
	s_mul_i32 s4, s3, -7
	s_sub_i32 s4, s4, s6
	s_add_i32 s7, s4, 0x208
	s_mov_b64 s[4:5], 0
	s_branch .LBB0_978

.LBB0_1048:
	s_sub_i32 s0, s80, s83
	s_add_i32 s1, s0, 1
	s_max_i32 s1, s1, 0
	s_max_i32 s0, s0, 0
	s_lshl_b32 s1, s1, 2
	s_add_i32 s1, s1, 0x24900
	v_mov_b32_e32 v33, s1
	ds_read_b32 v33, v33
	s_lshl_b32 s0, s0, 2
	s_add_i32 s0, s0, 0x24900
	v_mov_b32_e32 v34, s0
	ds_read_b32 v34, v34
	s_and_b32 s0, s81, 0x80
	s_mulk_i32 s0, 0xa0
	v_add_u32_e32 v32, s0, v151
	s_waitcnt vmcnt(3)
	ds_write_b128 v32, v[20:23]
	v_add_u32_e32 v20, s0, v152
	s_add_i32 s0, s81, 64
	s_and_b32 s0, s0, 0xc0
	v_add_u32_e32 v20, 0xa000, v20
	s_mulk_i32 s0, 0xa0
	s_waitcnt vmcnt(2)
	ds_write2_b64 v20, v[16:17], v[18:19] offset1:2
	v_add_u32_e32 v16, s0, v151
	s_waitcnt vmcnt(1)
	ds_write_b128 v16, v[28:31]
	v_add_u32_e32 v16, s0, v152
	s_add_i32 s0, s83, -1
	s_cmp_lt_u32 s0, s79
	s_cselect_b32 s0, s0, s80
	s_lshl_b32 s0, s0, 2
	s_add_i32 s22, 0, 0x24900
	v_add_u32_e32 v16, 0xa000, v16
	s_add_i32 s0, s22, s0
	s_waitcnt vmcnt(0)
	ds_write2_b64 v16, v[24:25], v[26:27] offset1:2
	s_waitcnt lgkmcnt(4)
	v_readfirstlane_b32 s98, v33
	v_readfirstlane_b32 s99, v34
	s_addk_i32 s81, 0x80
	s_add_i32 s82, s82, 8
	s_add_i32 s1, s83, -1
	s_cmp_ge_u32 s1, s79
	s_cbranch_scc1 .Lsel_skip_pf
	s_lshl_b32 s0, s98, 6
	s_ashr_i32 s1, s0, 31
	s_lshl_b64 s[20:21], s[0:1], 12
	v_lshl_add_u64 v[18:19], s[0:1], 1, v[148:149]
	v_lshl_add_u64 v[16:17], v[120:121], 0, s[20:21]
	global_load_dwordx4 v[20:23], v[16:17], off offset:2560
	s_nop 0
	global_load_dwordx4 v[16:19], v[18:19], off
	s_lshl_b32 s0, s99, 6
	s_ashr_i32 s1, s0, 31
	s_lshl_b64 s[20:21], s[0:1], 12
	v_lshl_add_u64 v[24:25], v[120:121], 0, s[20:21]
	v_lshl_add_u64 v[26:27], s[0:1], 1, v[148:149]
	global_load_dwordx4 v[28:31], v[24:25], off offset:2560
	s_nop 0
	global_load_dwordx4 v[24:27], v[26:27], off

.LBB0_1074:
	s_setprio 0
	s_cmp_gt_i32 s95, 13
	s_cselect_b64 s[4:5], -1, 0
	s_and_b64 s[0:1], s[34:35], s[4:5]
	s_andn2_b64 vcc, exec, s[0:1]
	s_cbranch_vccnz .LBB0_1128
	s_waitcnt vmcnt(0)
	s_waitcnt vmcnt(0) lgkmcnt(0)
	s_barrier
	s_and_saveexec_b64 s[0:1], s[50:51]
	s_cbranch_execz .LBB0_1127
	s_add_i32 s3, 0, 0x27fc0
	v_mov_b32_e32 v0, s3
	s_waitcnt vmcnt(0) expcnt(0) lgkmcnt(0)
	ds_read_b32 v2, v0
	s_add_i32 s3, 0, 0x27fc4
	v_mov_b32_e32 v0, s3
	ds_read_b32 v0, v0
	s_waitcnt lgkmcnt(1)
	v_cmp_ne_u32_e32 vcc, 0, v2
	s_cbranch_vccnz .LBB0_1091
	s_add_u32 s6, s92, 0x3800200
	s_addc_u32 s7, s93, 0
	s_add_u32 s8, s92, 0x3800400
	s_addc_u32 s9, s93, 0
	s_add_u32 s10, s92, 0x3800500
	s_addc_u32 s11, s93, 0
	s_add_u32 s12, s92, 0x3800600
	s_addc_u32 s13, s93, 0
	s_add_u32 s14, s92, 0x3800700
	s_addc_u32 s15, s93, 0
	s_add_u32 s16, s92, 0x3800800
	s_addc_u32 s17, s93, 0
	s_add_u32 s18, s92, 0x3800900
	s_addc_u32 s19, s93, 0
	s_add_u32 s20, s92, 0x3800a00
	s_addc_u32 s21, s93, 0
	s_add_u32 s22, s92, 0x3800b00
	s_addc_u32 s23, s93, 0
	s_add_u32 s24, s92, 0x3800c00
	s_addc_u32 s25, s93, 0
	s_add_u32 s26, s92, 0x3800d00
	s_addc_u32 s27, s93, 0
	s_add_u32 s28, s92, 0x3800e00
	s_addc_u32 s29, s93, 0
	s_add_u32 s30, s92, 0x3800f00
	s_addc_u32 s31, s93, 0
	s_add_u32 s34, s92, 0x3801000
	s_addc_u32 s35, s93, 0
	s_add_u32 s36, s92, 0x3801100
	s_addc_u32 s37, s93, 0
	s_add_u32 s38, s92, 0x3801200
	v_readlane_b32 s3, v236, 8
	s_addc_u32 s39, s93, 0
	s_mul_i32 s3, s85, s3
	s_add_u32 s40, s92, 0x3801300
	s_mul_i32 s3, s3, s84
	s_addc_u32 s41, s93, 0
	s_mov_b32 s48, 1
	v_mov_b32_e32 v16, 0
	s_branch .LBB0_1079
